# prologue: fold item (executed copy) issues first w_in chunk + peeled 8th loads early; transposes on idle WGs 224-255
# speedup vs baseline: 1.0070x; 1.0070x over previous
; #define LAS __attribute__((address_space(3)))
; __device__ __forceinline__ void p0_fold_item(const Params& p, LAS unsigned char* lds, int item) {
;     ...
;     for (int u = tid; u < 4096; u += NTHREADS) *(LAS f32x4*)(Wf + 4 * u) = *(const f32x4*)(p.w_four + (size_t)g * 16384 + 4 * u);
;     __syncthreads();
;     {
;         const int mt = w >> 1, nt0 = (w & 1) * 2, li = lane & 31, lk = lane >> 5, c = mt * 32 + li;
;         f32x16 acc0, acc1;
; #pragma unroll
;         for (int r = 0; r < 16; ++r) { acc0[r] = 0.f; acc1[r] = 0.f; }
; #pragma unroll 4
;         for (int ks = 0; ks < 64; ++ks) { const int e = 2 * ks + lk; const float ang = (float)((c * e) & 127) * (1.0f / 128.0f);
;             const float a = (which ? __builtin_amdgcn_sinf(ang) : __builtin_amdgcn_cosf(ang)) * 0.08838834764831845f;
;             const float b0 = Wf[e * 128 + nt0 * 32 + li], b1 = Wf[e * 128 + nt0 * 32 + 32 + li];
;             acc0 = __builtin_amdgcn_mfma_f32_32x32x2f32(a, b0, acc0, 0, 0, 0); acc1 = __builtin_amdgcn_mfma_f32_32x32x2f32(a, b1, acc1, 0, 0, 0); }
; #pragma unroll
;         for (int r = 0; r < 16; ++r) { const int row = mt * 32 + (r & 3) + 8 * (r >> 2) + 4 * lk; Gm[row * 128 + nt0 * 32 + li] = acc0[r]; Gm[row * 128 + nt0 * 32 + 32 + li] = acc1[r]; }
;     }
;     for (int sub = 0; sub < 2; ++sub) { const int i0 = ib + sub * 32;
;     for (int u = tid; u < 4096; u += NTHREADS) { const int il = u >> 7, c = u & 127; wt[il * 129 + c] = p.w_in[(size_t)(i0 + il) * 2048 + g * 128 + c]; }
.LBB0_62:
	s_andn2_b64 vcc, exec, s[4:5]
	s_cbranch_vccnz .LBB0_76
	s_bfe_u32 s10, s2, 0x20004
	s_lshl_b32 s4, s10, 16
	s_waitcnt lgkmcnt(0)
	s_add_u32 s4, s48, s4
	v_mov_b32_e32 v0, 0
	s_addc_u32 s5, s49, 0
	v_lshlrev_b32_e32 v32, 4, v170
	v_mov_b32_e32 v33, v0
	v_lshl_add_u64 v[2:3], s[4:5], 0, v[32:33]
	v_add_co_u32_e32 v16, vcc, 0x2000, v2
	v_or_b32_e32 v1, 0x4000, v32
	s_nop 0
	v_addc_co_u32_e32 v17, vcc, 0, v3, vcc
	v_add_co_u32_e32 v24, vcc, 0x6000, v2
	v_or_b32_e32 v33, 0xc00, v170
	s_nop 0
	v_addc_co_u32_e32 v25, vcc, 0, v3, vcc
	v_add_co_u32_e32 v34, vcc, 0xa000, v2
	global_load_dwordx4 v[4:7], v32, s[4:5]
	s_nop 0
	v_addc_co_u32_e32 v35, vcc, 0, v3, vcc
	global_load_dwordx4 v[8:11], v[16:17], off
	global_load_dwordx4 v[12:15], v1, s[4:5]
	v_or_b32_e32 v1, 0x8000, v32
	global_load_dwordx4 v[16:19], v[24:25], off
	global_load_dwordx4 v[20:23], v1, s[4:5]
	v_lshlrev_b32_e32 v41, 4, v33
	global_load_dwordx4 v[24:27], v[34:35], off
	global_load_dwordx4 v[28:31], v41, s[4:5]
	v_add_co_u32_e32 v208, vcc, 0xe000, v2
	s_nop 1
	v_addc_co_u32_e32 v209, vcc, 0, v3, vcc
	s_movk_i32 s98, 0xe00
	v_cmp_gt_u32_e32 vcc, s98, v33
	s_and_saveexec_b64 s[98:99], vcc
	global_load_dwordx4 v[204:207], v[208:209], off
	s_or_b64 exec, exec, s[98:99]
	s_movk_i32 s4, 0xe00
	s_mov_b32 s11, 0
	v_add_u32_e32 v1, 0, v32
	v_cmp_gt_u32_e64 s[4:5], s4, v33
	v_add_u32_e32 v32, 0, v41
	s_waitcnt vmcnt(7)
	ds_write_b128 v1, v[4:7]
	s_waitcnt vmcnt(6)
	ds_write_b128 v1, v[8:11] offset:8192
	s_waitcnt vmcnt(5)
	ds_write_b128 v1, v[12:15] offset:16384
	s_waitcnt vmcnt(4)
	ds_write_b128 v1, v[16:19] offset:24576
	s_waitcnt vmcnt(3)
	ds_write_b128 v1, v[20:23] offset:32768
	s_waitcnt vmcnt(2)
	ds_write_b128 v1, v[24:27] offset:40960
	s_waitcnt vmcnt(1)
	ds_write_b128 v32, v[28:31]
	s_and_saveexec_b64 s[12:13], s[4:5]
	s_xor_b64 s[12:13], exec, s[12:13]
	s_cbranch_execz .LBB0_65
	s_waitcnt vmcnt(0)
	ds_write_b128 v1, v[204:207] offset:57344
.LBB0_65:
	s_or_b64 exec, exec, s[12:13]
	v_lshrrev_b32_e32 v232, 7, v170
	s_and_b32 s98, s17, 0x3c0
	v_or_b32_e32 v204, s98, v232
	v_or_b32_e32 v210, 8, v232
	s_lshl_b32 s99, s10, 7
	v_lshlrev_b32_e32 v204, 11, v204
	v_or_b32_e32 v211, s98, v210
	v_or3_b32 v204, v109, v204, s99
	v_lshlrev_b32_e32 v211, 11, v211
	v_lshlrev_b32_e32 v208, 2, v204
	v_add_u32_e32 v204, 0x200, v170
	v_or3_b32 v211, v109, v211, s99
	v_lshrrev_b32_e32 v209, 7, v204
	v_lshlrev_b32_e32 v220, 2, v211
	v_add_u32_e32 v211, 0x600, v170
	v_or_b32_e32 v204, s98, v209
	v_lshrrev_b32_e32 v211, 7, v211
	v_lshlrev_b32_e32 v204, 11, v204
	v_or_b32_e32 v212, s98, v211
	v_or3_b32 v206, v109, v204, s99
	v_mov_b32_e32 v204, 0
	v_lshlrev_b32_e32 v212, 11, v212
	v_or3_b32 v212, v109, v212, s99
	v_mov_b32_e32 v213, v204
	v_lshl_add_u64 v[216:217], v[212:213], 2, s[46:47]
	v_or_b32_e32 v212, 16, v232
	v_or_b32_e32 v213, s98, v212
	v_lshlrev_b32_e32 v213, 11, v213
	v_or3_b32 v213, v109, v213, s99
	v_lshlrev_b32_e32 v221, 2, v213
	v_add_u32_e32 v213, 0xa00, v170
	v_lshrrev_b32_e32 v213, 7, v213
	v_or_b32_e32 v214, s98, v213
	v_lshlrev_b32_e32 v214, 11, v214
	v_or3_b32 v214, v109, v214, s99
	v_mov_b32_e32 v215, v204
	v_lshl_add_u64 v[218:219], v[214:215], 2, s[46:47]
	v_lshrrev_b32_e32 v214, 7, v33
	v_or_b32_e32 v205, s98, v214
	v_lshlrev_b32_e32 v205, 11, v205
	v_mov_b32_e32 v207, v204
	v_or3_b32 v205, v109, v205, s99
	v_lshl_add_u64 v[206:207], v[206:207], 2, s[46:47]
	v_lshlrev_b32_e32 v205, 2, v205
	global_load_dword v224, v208, s[46:47]
	global_load_dword v225, v[206:207], off
	global_load_dword v226, v220, s[46:47]
	global_load_dword v227, v[216:217], off
	global_load_dword v228, v221, s[46:47]
	global_load_dword v229, v[218:219], off
	global_load_dword v230, v205, s[46:47]
	v_add_u32_e32 v222, 0xe00, v170
	v_lshrrev_b32_e32 v222, 7, v222
	v_or_b32_e32 v222, s98, v222
	v_lshlrev_b32_e32 v222, 11, v222
	v_or3_b32 v222, v109, v222, s99
	v_mov_b32_e32 v223, 0
	v_lshl_add_u64 v[222:223], v[222:223], 2, s[46:47]
	s_and_saveexec_b64 s[98:99], s[4:5]
	global_load_dword v231, v[222:223], off
	s_or_b64 exec, exec, s[98:99]
	v_lshl_or_b32 v1, v106, 9, v119
	v_add3_u32 v32, v1, v36, 0
	v_add_u32_e32 v1, v118, v107
	v_or_b32_e32 v2, 6, v106
	v_mul_u32_u24_e32 v34, v1, v2
	v_lshrrev_b32_e32 v42, 7, v170
	v_lshlrev_b32_e32 v2, 3, v107
	v_lshl_or_b32 v35, v42, 8, v2
	v_or_b32_e32 v2, 4, v106
	s_cmp_lt_u32 s2, 64
	v_mul_u32_u24_e32 v41, v1, v2
	v_or_b32_e32 v2, 2, v106
	s_cselect_b64 vcc, -1, 0
	v_mul_u32_u24_e32 v43, v1, v2
	v_mul_u32_u24_e32 v44, v106, v1
	v_mov_b32_e32 v45, 0
	v_mov_b32_e32 v1, v0
	v_mov_b32_e32 v2, v0
	v_mov_b32_e32 v3, v0
	v_mov_b32_e32 v4, v0
	v_mov_b32_e32 v5, v0
	v_mov_b32_e32 v6, v0
	v_mov_b32_e32 v7, v0
	v_mov_b32_e32 v8, v0
	v_mov_b32_e32 v9, v0
	v_mov_b32_e32 v10, v0
	v_mov_b32_e32 v11, v0
	v_mov_b32_e32 v12, v0
	v_mov_b32_e32 v13, v0
	v_mov_b32_e32 v14, v0
	v_mov_b32_e32 v15, v0
	v_mov_b32_e32 v16, v0
	v_mov_b32_e32 v17, v0
	v_mov_b32_e32 v18, v0
	v_mov_b32_e32 v19, v0
	v_mov_b32_e32 v20, v0
	v_mov_b32_e32 v21, v0
	v_mov_b32_e32 v22, v0
	v_mov_b32_e32 v23, v0
	v_mov_b32_e32 v24, v0
	v_mov_b32_e32 v25, v0
	v_mov_b32_e32 v26, v0
	v_mov_b32_e32 v27, v0
	v_mov_b32_e32 v28, v0
	v_mov_b32_e32 v29, v0
	v_mov_b32_e32 v30, v0
	v_mov_b32_e32 v31, v0
	s_waitcnt lgkmcnt(0)
	s_barrier
; __device__ __forceinline__ void p0_fold_item(const Params& p, LAS unsigned char* lds, int item) {
;     ...
; #pragma unroll 4
;         for (int ks = 0; ks < 64; ++ks) { const int e = 2 * ks + lk; const float ang = (float)((c * e) & 127) * (1.0f / 128.0f);
;             const float a = (which ? __builtin_amdgcn_sinf(ang) : __builtin_amdgcn_cosf(ang)) * 0.08838834764831845f;
;             const float b0 = Wf[e * 128 + nt0 * 32 + li], b1 = Wf[e * 128 + nt0 * 32 + 32 + li];
;             acc0 = __builtin_amdgcn_mfma_f32_32x32x2f32(a, b0, acc0, 0, 0, 0); acc1 = __builtin_amdgcn_mfma_f32_32x32x2f32(a, b1, acc1, 0, 0, 0); }
; #pragma unroll
;         for (int r = 0; r < 16; ++r) { const int row = mt * 32 + (r & 3) + 8 * (r >> 2) + 4 * lk; Gm[row * 128 + nt0 * 32 + li] = acc0[r]; Gm[row * 128 + nt0 * 32 + 32 + li] = acc1[r]; }
;     }
;     for (int sub = 0; sub < 2; ++sub) { const int i0 = ib + sub * 32;
;     for (int u = tid; u < 4096; u += NTHREADS) { const int il = u >> 7, c = u & 127; wt[il * 129 + c] = p.w_in[(size_t)(i0 + il) * 2048 + g * 128 + c]; }
.LBB0_66:
	v_add_u32_e32 v46, v44, v45
	v_and_b32_e32 v49, 0x7f, v46
	v_cvt_f32_ubyte0_e32 v49, v49
	v_mul_f32_e32 v49, 0x3c000000, v49
	v_sin_f32_e32 v50, v49
	v_cos_f32_e32 v49, v49
	v_add_u32_e32 v48, s11, v32
	ds_read2_b32 v[46:47], v48 offset1:32
	s_addk_i32 s11, 0x1000
	v_cndmask_b32_e32 v49, v50, v49, vcc
	v_mul_f32_e32 v49, 0x3db504f3, v49
	s_cmp_eq_u32 s11, 0x10000
	s_waitcnt lgkmcnt(0)
	v_mfma_f32_32x32x2_f32 v[0:15], v49, v46, v[0:15]
	v_add_u32_e32 v46, v43, v45
	v_and_b32_e32 v46, 0x7f, v46
	v_mfma_f32_32x32x2_f32 v[16:31], v49, v47, v[16:31]
	v_cvt_f32_ubyte0_e32 v49, v46
	v_mul_f32_e32 v49, 0x3c000000, v49
	v_sin_f32_e32 v50, v49
	v_cos_f32_e32 v49, v49
	v_add_u32_e32 v47, 0x400, v48
	ds_read2_b32 v[46:47], v47 offset1:32
	v_cndmask_b32_e32 v49, v50, v49, vcc
	v_mul_f32_e32 v49, 0x3db504f3, v49
	s_waitcnt lgkmcnt(0)
	s_nop 0
	v_mfma_f32_32x32x2_f32 v[0:15], v49, v46, v[0:15]
	v_add_u32_e32 v46, v41, v45
	v_and_b32_e32 v46, 0x7f, v46
	v_mfma_f32_32x32x2_f32 v[16:31], v49, v47, v[16:31]
	v_cvt_f32_ubyte0_e32 v49, v46
	v_mul_f32_e32 v49, 0x3c000000, v49
	v_sin_f32_e32 v50, v49
	v_cos_f32_e32 v49, v49
	v_add_u32_e32 v47, 0x800, v48
	ds_read2_b32 v[46:47], v47 offset1:32
	v_cndmask_b32_e32 v49, v50, v49, vcc
	v_mul_f32_e32 v49, 0x3db504f3, v49
	s_waitcnt lgkmcnt(0)
	s_nop 0
	v_mfma_f32_32x32x2_f32 v[0:15], v49, v46, v[0:15]
	v_add_u32_e32 v46, v34, v45
	v_and_b32_e32 v46, 0x7f, v46
	v_add_u32_e32 v45, v45, v35
	v_mfma_f32_32x32x2_f32 v[16:31], v49, v47, v[16:31]
	v_add_u32_e32 v47, 0xc00, v48
	v_cvt_f32_ubyte0_e32 v48, v46
	v_mul_f32_e32 v48, 0x3c000000, v48
	v_sin_f32_e32 v49, v48
	v_cos_f32_e32 v48, v48
	ds_read2_b32 v[46:47], v47 offset1:32
	v_cndmask_b32_e32 v48, v49, v48, vcc
	v_mul_f32_e32 v48, 0x3db504f3, v48
	s_waitcnt lgkmcnt(0)
	s_nop 0
	v_mfma_f32_32x32x2_f32 v[0:15], v48, v46, v[0:15]
	v_mfma_f32_32x32x2_f32 v[16:31], v48, v47, v[16:31]
	s_cbranch_scc0 .LBB0_66
	s_and_b32 s11, s17, 0x3c0
	v_or_b32_e32 v32, s11, v42
	v_or_b32_e32 v44, 8, v42
	s_lshl_b32 s10, s10, 7
	v_lshlrev_b32_e32 v32, 11, v32
	v_or_b32_e32 v45, s11, v44
	v_or3_b32 v32, v109, v32, s10
	v_lshlrev_b32_e32 v45, 11, v45
	v_lshlrev_b32_e32 v41, 2, v32
	v_add_u32_e32 v32, 0x200, v170
	v_or3_b32 v45, v109, v45, s10
	v_lshrrev_b32_e32 v43, 7, v32
	v_lshlrev_b32_e32 v54, 2, v45
	v_add_u32_e32 v45, 0x600, v170
	v_or_b32_e32 v32, s11, v43
	v_lshrrev_b32_e32 v45, 7, v45
	v_lshlrev_b32_e32 v32, 11, v32
	v_or_b32_e32 v46, s11, v45
	v_or3_b32 v34, v109, v32, s10
	v_mov_b32_e32 v32, 0
	v_lshlrev_b32_e32 v46, 11, v46
	v_or3_b32 v46, v109, v46, s10
	v_mov_b32_e32 v47, v32
	v_lshl_add_u64 v[50:51], v[46:47], 2, s[46:47]
	v_or_b32_e32 v46, 16, v42
	v_or_b32_e32 v47, s11, v46
	v_lshlrev_b32_e32 v47, 11, v47
	v_or3_b32 v47, v109, v47, s10
	v_lshlrev_b32_e32 v55, 2, v47
	v_add_u32_e32 v47, 0xa00, v170
	v_lshrrev_b32_e32 v47, 7, v47
	v_or_b32_e32 v48, s11, v47
	v_lshlrev_b32_e32 v48, 11, v48
	v_or3_b32 v48, v109, v48, s10
	v_mov_b32_e32 v49, v32
	v_lshl_add_u64 v[52:53], v[48:49], 2, s[46:47]
	v_lshrrev_b32_e32 v48, 7, v33
	v_or_b32_e32 v33, s11, v48
	v_lshlrev_b32_e32 v33, 11, v33
	v_mov_b32_e32 v35, v32
	v_or3_b32 v33, v109, v33, s10
	v_lshl_add_u64 v[34:35], v[34:35], 2, s[46:47]
	v_lshlrev_b32_e32 v33, 2, v33
	v_add_u32_e32 v33, v117, v116
	s_movk_i32 s14, 0x204
	ds_write2_b32 v33, v0, v16 offset1:32
	ds_write2_b32 v33, v1, v17 offset0:128 offset1:160
	v_add_u32_e32 v0, 0x400, v33
	v_add_u32_e32 v1, 0x1000, v33
	v_mad_u32_u24 v41, v42, s14, v108
	v_add_u32_e32 v16, 0x1400, v33
	v_add_u32_e32 v17, 0x2000, v33
	v_add_u32_e32 v34, 0x2400, v33
	v_add_u32_e32 v35, 0x3000, v33
	v_add_u32_e32 v33, 0x3400, v33
	v_mad_u32_u24 v50, v48, s14, v108
	ds_write2_b32 v0, v2, v18 offset1:32
	ds_write2_b32 v0, v3, v19 offset0:128 offset1:160
	ds_write2_b32 v1, v4, v20 offset1:32
	ds_write2_b32 v1, v5, v21 offset0:128 offset1:160
	ds_write2_b32 v16, v6, v22 offset1:32
	ds_write2_b32 v16, v7, v23 offset0:128 offset1:160
	ds_write2_b32 v17, v8, v24 offset1:32
	ds_write2_b32 v17, v9, v25 offset0:128 offset1:160
	ds_write2_b32 v34, v10, v26 offset1:32
	ds_write2_b32 v34, v11, v27 offset0:128 offset1:160
	ds_write2_b32 v35, v12, v28 offset1:32
	ds_write2_b32 v35, v13, v29 offset0:128 offset1:160
	ds_write2_b32 v33, v14, v30 offset1:32
	ds_write2_b32 v33, v15, v31 offset0:128 offset1:160
	v_mad_u32_u24 v0, v43, s14, v108
	v_mad_u32_u24 v1, v45, s14, v108
	v_mad_u32_u24 v2, v47, s14, v108
	s_waitcnt vmcnt(0)
	ds_write_b32 v41, v224
	s_waitcnt vmcnt(5)
	ds_write_b32 v0, v225
	s_waitcnt vmcnt(4)
	ds_write_b32 v41, v226 offset:4128
	s_waitcnt vmcnt(3)
	ds_write_b32 v1, v227
	s_waitcnt vmcnt(2)
	ds_write_b32 v41, v228 offset:8256
	s_waitcnt vmcnt(1)
	ds_write_b32 v2, v229
	s_waitcnt vmcnt(0)
	ds_write_b32 v50, v230
	s_and_saveexec_b64 s[12:13], s[4:5]
	s_cbranch_execz .LBB0_69
	v_add_u32_e32 v0, 0xe00, v170
	v_lshrrev_b32_e32 v2, 7, v0
	v_mad_u32_u24 v1, v2, s14, v108
	ds_write_b32 v1, v231
